# attention PV regions regenerated: MFMA order ks-outer, V-fragment reads 7 ahead in VALU-free slots, mask/row-max VALU spread over the MFMA gaps (was trailing the MFMAs)
# speedup vs baseline: 1.0226x; 1.0042x over previous
; __device__ __forceinline__ void finishSM(f32x16& p0, f32x16& p1, float alpha, float& l_reg, bf16x8& pa0, bf16x8& pa1, bf16x8& pa2, bf16x8& pa3) {
; #pragma unroll
;     for (int r = 0; r < 16; ++r) p1[r] = __builtin_amdgcn_exp2f(p1[r]);
;     float ps = 0;
; #pragma unroll
;     for (int r = 0; r < 16; ++r) ps += p0[r];
; #pragma unroll
;     for (int r = 0; r < 16; ++r) ps += p1[r];
;     { auto rr = __builtin_amdgcn_permlane32_swap(__float_as_uint(ps), __float_as_uint(ps), false, false);
;       ps = __uint_as_float(rr[0]) + __uint_as_float(rr[1]); }
;     l_reg = l_reg * alpha + ps;
;     ...
;     PK4(p0, 0, pa0); PK4(p0, 8, pa1); PK4(p1, 0, pa2); PK4(p1, 8, pa3);
;     ...
; }
; template <int KB>
; __device__ __forceinline__ void qkt(f32x16& p0, f32x16& p1, const char* K_lds, int r32, int hi, const bf16x8* qr) {
;     p0 = f32x16{}; p1 = f32x16{};
;     const char* kb[4];
; #pragma unroll
;     for (int dd = 0; dd < 4; ++dd) kb[dd] = K_lds + KB * SHM_K + KSWZ(r32, (dd * 16 + hi * 8) * 2);
; #pragma unroll
;     for (int d0 = 0; d0 < 8; ++d0) { const char* a = kb[d0 & 3] + (d0 >> 2) * 128;
;         bf16x8 b0 = *reinterpret_cast<const bf16x8*>(a);
;         bf16x8 b1 = *reinterpret_cast<const bf16x8*>(a + 32 * 256);
;         p0 = __builtin_amdgcn_mfma_f32_32x32x16_bf16(b0, qr[d0], p0, 0, 0, 0);
;         p1 = __builtin_amdgcn_mfma_f32_32x32x16_bf16(b1, qr[d0], p1, 0, 0, 0); }
; }
; template <int VB>
; __device__ __forceinline__ void pv_tile(f32x16* o, int vb0, bf16x8 pa0, bf16x8 pa1, bf16x8 pa2, bf16x8 pa3) {
;     ...
;     PV_D0(0); PV_D0(1); PV_D0(2); PV_D0(3);
.LBB0_1299:
	v_add_u32_e32 v146, -8, v179
	global_load_dwordx2 v[146:147], v146, s[68:69]
	v_lshl_add_u64 v[130:131], v[188:189], 0, v[170:171]
	v_lshl_add_u64 v[138:139], v[190:191], 0, v[170:171]
	v_lshl_add_u64 v[134:135], v[130:131], 0, s[100:101]
	v_lshl_add_u64 v[130:131], v[130:131], 0, s[16:17]
	v_lshl_add_u64 v[142:143], v[138:139], 0, s[100:101]
	v_lshl_add_u64 v[138:139], v[138:139], 0, s[16:17]
	global_load_dwordx4 v[130:133], v[130:131], off
	global_load_dwordx4 v[134:137], v[134:135], off
	global_load_dwordx4 v[138:141], v[138:139], off
	global_load_dwordx4 v[142:145], v[142:143], off
	ds_read_b128 v[66:69], v199 offset:49152
	ds_read_b128 v[82:85], v199 offset:57344
	ds_read_b128 v[172:175], v200 offset:49152
	ds_read_b128 v[232:235], v200 offset:57344
	ds_read_b128 v[236:239], v201 offset:49152
	ds_read_b128 v[240:243], v201 offset:57344
	ds_read_b128 v[244:247], v202 offset:49152
	v_exp_f32_e32 v209, v150
	v_add_f32_e32 v150, 0, v219
	v_add_f32_e32 v150, v220, v150
	v_add_f32_e32 v150, v221, v150
	s_waitcnt lgkmcnt(6)
	v_mfma_f32_32x32x16_bf16 v[66:81], v[66:69], v[126:129], 0
	v_add_f32_e32 v150, v222, v150
	v_add_f32_e32 v150, v223, v150
	v_add_f32_e32 v150, v225, v150
	v_add_f32_e32 v150, v224, v150
	v_add_f32_e32 v150, v226, v150
	s_waitcnt lgkmcnt(5)
	v_mfma_f32_32x32x16_bf16 v[82:97], v[82:85], v[126:129], 0
	v_add_f32_e32 v150, v211, v150
	v_add_f32_e32 v150, v212, v150
	v_exp_f32_e32 v194, v194
	s_waitcnt lgkmcnt(4)
	v_mfma_f32_32x32x16_bf16 v[66:81], v[172:175], v[122:125], v[66:81]
	ds_read_b128 v[172:175], v202 offset:57344
	v_exp_f32_e32 v195, v195
	v_exp_f32_e32 v192, v192
	v_exp_f32_e32 v193, v193
	s_waitcnt lgkmcnt(4)
	v_mfma_f32_32x32x16_bf16 v[82:97], v[232:235], v[122:125], v[82:97]
	ds_read_b128 v[232:235], v199 offset:49280
	v_exp_f32_e32 v158, v158
	v_exp_f32_e32 v159, v159
	s_waitcnt lgkmcnt(4)
	v_mfma_f32_32x32x16_bf16 v[66:81], v[236:239], v[118:121], v[66:81]
	ds_read_b128 v[236:239], v199 offset:57472
	v_exp_f32_e32 v207, v154
	v_exp_f32_e32 v208, v155
	v_exp_f32_e32 v210, v151
	s_waitcnt lgkmcnt(4)
	v_mfma_f32_32x32x16_bf16 v[82:97], v[240:243], v[118:121], v[82:97]
	ds_read_b128 v[240:243], v200 offset:49280
	v_exp_f32_e32 v160, v160
	v_exp_f32_e32 v161, v161
	s_waitcnt lgkmcnt(4)
	v_mfma_f32_32x32x16_bf16 v[66:81], v[244:247], v[114:117], v[66:81]
	ds_read_b128 v[244:247], v200 offset:57472
	v_exp_f32_e32 v227, v156
	v_cvt_pk_bf16_f32 v151, v224, v226
	v_cvt_pk_bf16_f32 v154, v214, v216
	v_cvt_pk_bf16_f32 v155, v217, v218
	v_cvt_pk_bf16_f32 v156, v194, v195
	s_waitcnt lgkmcnt(4)
	v_mfma_f32_32x32x16_bf16 v[82:97], v[172:175], v[114:117], v[82:97]
	ds_read_b128 v[172:175], v201 offset:49280
	v_exp_f32_e32 v228, v157
	v_exp_f32_e32 v229, v152
	s_waitcnt lgkmcnt(4)
	v_mfma_f32_32x32x16_bf16 v[66:81], v[232:235], v[110:113], v[66:81]
	ds_read_b128 v[232:235], v201 offset:57472
	v_exp_f32_e32 v230, v153
	v_cvt_pk_bf16_f32 v152, v211, v212
	v_cvt_pk_bf16_f32 v153, v213, v215
	v_cvt_pk_bf16_f32 v157, v192, v193
	v_cvt_pk_bf16_f32 v211, v229, v230
	s_waitcnt lgkmcnt(4)
	v_mfma_f32_32x32x16_bf16 v[82:97], v[236:239], v[110:113], v[82:97]
	ds_read_b128 v[236:239], v202 offset:49280
	v_permlane32_swap_b32_e32 v152, v154
	v_permlane32_swap_b32_e32 v153, v155
	v_add_f32_e32 v249, v213, v150
	v_add_f32_e32 v249, v215, v249
	v_add_f32_e32 v249, v214, v249
	s_waitcnt lgkmcnt(4)
	v_mfma_f32_32x32x16_bf16 v[66:81], v[240:243], v[106:109], v[66:81]
	ds_read_b128 v[240:243], v202 offset:57472
	v_add_f32_e32 v249, v216, v249
	v_add_f32_e32 v249, v217, v249
	v_add_f32_e32 v249, v218, v249
	v_add_f32_e32 v249, v194, v249
	v_add_f32_e32 v248, v195, v249
	s_waitcnt lgkmcnt(4)
	v_mfma_f32_32x32x16_bf16 v[82:97], v[244:247], v[106:109], v[82:97]
	v_add_f32_e32 v248, v192, v248
	v_add_f32_e32 v248, v193, v248
	v_add_f32_e32 v248, v158, v248
	v_add_f32_e32 v248, v159, v248
	v_add_f32_e32 v248, v207, v248
	s_waitcnt lgkmcnt(3)
	v_mfma_f32_32x32x16_bf16 v[66:81], v[172:175], v[102:105], v[66:81]
	v_add_f32_e32 v248, v208, v248
	v_add_f32_e32 v248, v209, v248
	v_add_f32_e32 v248, v210, v248
	v_add_f32_e32 v248, v160, v248
	v_add_f32_e32 v248, v161, v248
	s_waitcnt lgkmcnt(2)
	v_mfma_f32_32x32x16_bf16 v[82:97], v[232:235], v[102:105], v[82:97]
	v_add_f32_e32 v248, v227, v248
	v_add_f32_e32 v248, v228, v248
	v_add_f32_e32 v248, v229, v248
	v_add_f32_e32 v181, v230, v248
	v_mov_b32_e32 v187, v181
	s_waitcnt lgkmcnt(1)
	v_mfma_f32_32x32x16_bf16 v[66:81], v[236:239], v[98:101], v[66:81]
	v_cvt_pk_bf16_f32 v148, v219, v220
	v_cvt_pk_bf16_f32 v149, v221, v222
	v_cvt_pk_bf16_f32 v150, v223, v225
	v_cvt_pk_bf16_f32 v158, v158, v159
	v_cvt_pk_bf16_f32 v159, v207, v208
	s_waitcnt lgkmcnt(0)
	v_mfma_f32_32x32x16_bf16 v[82:97], v[240:243], v[98:101], v[82:97]
	v_cvt_pk_bf16_f32 v208, v209, v210
	v_cvt_pk_bf16_f32 v210, v227, v228
	v_permlane32_swap_b32_e32 v181, v187
	v_permlane32_swap_b32_e32 v148, v150
	v_permlane32_swap_b32_e32 v149, v151
	v_cvt_pk_bf16_f32 v209, v160, v161
	v_permlane32_swap_b32_e32 v208, v210
	v_permlane32_swap_b32_e32 v156, v158
	v_permlane32_swap_b32_e32 v157, v159
	v_permlane32_swap_b32_e32 v209, v211
	v_lshl_add_u64 v[194:195], v[188:189], 0, v[170:171]
	v_lshl_add_u64 v[192:193], v[190:191], 0, v[170:171]
	ds_read_b64_tr_b16 v[172:173], v1 offset:0x0
	ds_read_b64_tr_b16 v[174:175], v1 offset:0x800
	ds_read_b64_tr_b16 v[212:213], v1 offset:0x200
	ds_read_b64_tr_b16 v[214:215], v1 offset:0xa00
	ds_read_b64_tr_b16 v[216:217], v1 offset:0x400
	ds_read_b64_tr_b16 v[218:219], v1 offset:0xc00
	ds_read_b64_tr_b16 v[220:221], v1 offset:0x600
	ds_read_b64_tr_b16 v[222:223], v1 offset:0xe00
	ds_read_b64_tr_b16 v[224:225], v1 offset:0x1000
	ds_read_b64_tr_b16 v[226:227], v1 offset:0x1800
	ds_read_b64_tr_b16 v[232:233], v1 offset:0x1200
	ds_read_b64_tr_b16 v[234:235], v1 offset:0x1a00
	ds_read_b64_tr_b16 v[236:237], v1 offset:0x1400
	ds_read_b64_tr_b16 v[238:239], v1 offset:0x1c00
	s_nop 0
	s_waitcnt lgkmcnt(12)
; __device__ __forceinline__ void sel_mask_tile(f32x16& p0, f32x16& p1, unsigned wlo, unsigned whi, int hi) {
;     const unsigned NEGB = 0xff800000u;
;     const unsigned lo = wlo >> (4 * hi), h2 = whi >> (4 * hi);
; #pragma unroll
;     for (int r = 0; r < 16; ++r) {
;         const int c = (r & 3) + 8 * (r >> 2);
;         const unsigned m0 = (unsigned)__builtin_amdgcn_sbfe((int)lo, c, 1), m1 = (unsigned)__builtin_amdgcn_sbfe((int)h2, c, 1);
;         p0[r] = __uint_as_float((__float_as_uint(p0[r]) & m0) | (NEGB & ~m0));
;         p1[r] = __uint_as_float((__float_as_uint(p1[r]) & m1) | (NEGB & ~m1));
;     }
; }
; __device__ __forceinline__ void partialSM(f32x16& p0, f32x16& p1, float& m_reg, float& mn, float& alpha) {
;     float pmax = p0[0];
; #pragma unroll
;     for (int r = 1; r < 16; ++r) pmax = fmaxf(pmax, p0[r]);
; #pragma unroll
;     for (int r = 0; r < 16; ++r) pmax = fmaxf(pmax, p1[r]);
;     { auto rr = __builtin_amdgcn_permlane32_swap(__float_as_uint(pmax), __float_as_uint(pmax), false, false);
;       pmax = fmaxf(__uint_as_float(rr[0]), __uint_as_float(rr[1])); }
;     constexpr float C2 = 1.4426950408889634f * SCALE;
;     if (__builtin_expect(__all((pmax - m_reg) * SCALE <= THR), 1)) { mn = m_reg; alpha = 1.f; }
;     else { mn = fmaxf(m_reg, pmax); alpha = __builtin_amdgcn_exp2f((m_reg - mn) * C2); m_reg = mn; }
; template <int VB>
; __device__ __forceinline__ void pv_tile(f32x16* o, int vb0, bf16x8 pa0, bf16x8 pa1, bf16x8 pa2, bf16x8 pa3) {
;     ...
;     PV_D0(0); PV_D0(1); PV_D0(2); PV_D0(3);
;     ...
; }
	v_mfma_f32_32x32x16_bf16 v[2:17], v[148:151], v[172:175], v[2:17]
	ds_read_b64_tr_b16 v[240:241], v1 offset:0x1600
	ds_read_b64_tr_b16 v[242:243], v1 offset:0x1e00
	s_waitcnt vmcnt(4)
	v_lshrrev_b32_e32 v160, v163, v146
	v_lshrrev_b32_e32 v161, v163, v147
	v_bfe_i32 v146, v160, 0, 1
	v_bfe_i32 v147, v161, 0, 1
	v_bitop3_b32 v146, v66, s74, v146 bitop3:0xe4
	v_bitop3_b32 v66, v82, s74, v147 bitop3:0xe4
	s_waitcnt lgkmcnt(12)
	v_mfma_f32_32x32x16_bf16 v[50:65], v[148:151], v[212:215], v[50:65]
	ds_read_b64_tr_b16 v[244:245], v1 offset:0x2000
	ds_read_b64_tr_b16 v[246:247], v1 offset:0x2800
	v_bfe_i32 v82, v160, 1, 1
	v_bfe_i32 v147, v161, 1, 1
	v_bitop3_b32 v82, v67, s74, v82 bitop3:0xe4
	v_bitop3_b32 v67, v83, s74, v147 bitop3:0xe4
	v_bfe_i32 v83, v160, 2, 1
	v_bfe_i32 v147, v161, 2, 1
	s_waitcnt lgkmcnt(12)
	v_mfma_f32_32x32x16_bf16 v[34:49], v[148:151], v[216:219], v[34:49]
	ds_read_b64_tr_b16 v[248:249], v1 offset:0x2200
	ds_read_b64_tr_b16 v[250:251], v1 offset:0x2a00
	v_bitop3_b32 v83, v68, s74, v83 bitop3:0xe4
	v_bitop3_b32 v68, v84, s74, v147 bitop3:0xe4
	v_bfe_i32 v84, v160, 3, 1
	s_waitcnt lgkmcnt(12)
	v_mfma_f32_32x32x16_bf16 v[18:33], v[148:151], v[220:223], v[18:33]
	ds_read_b64_tr_b16 v[220:221], v1 offset:0x2400
	ds_read_b64_tr_b16 v[222:223], v1 offset:0x2c00
	v_bfe_i32 v148, v161, 3, 1
	v_bitop3_b32 v147, v69, s74, v84 bitop3:0xe4
	v_bfe_i32 v84, v160, 8, 1
	v_bitop3_b32 v69, v85, s74, v148 bitop3:0xe4
	v_bfe_i32 v85, v161, 8, 1
	v_bitop3_b32 v148, v70, s74, v84 bitop3:0xe4
	v_bfe_i32 v84, v160, 9, 1
	s_waitcnt lgkmcnt(12)
	v_mfma_f32_32x32x16_bf16 v[2:17], v[152:155], v[224:227], v[2:17]
	ds_read_b64_tr_b16 v[224:225], v1 offset:0x2600
	ds_read_b64_tr_b16 v[226:227], v1 offset:0x2e00
	v_bitop3_b32 v70, v86, s74, v85 bitop3:0xe4
	v_bfe_i32 v85, v161, 9, 1
	v_bitop3_b32 v149, v71, s74, v84 bitop3:0xe4
	v_bfe_i32 v84, v160, 10, 1
	v_bitop3_b32 v71, v87, s74, v85 bitop3:0xe4
	v_bfe_i32 v85, v161, 10, 1
	s_waitcnt lgkmcnt(12)
	v_mfma_f32_32x32x16_bf16 v[50:65], v[152:155], v[232:235], v[50:65]
	ds_read_b64_tr_b16 v[232:233], v1 offset:0x3000
	ds_read_b64_tr_b16 v[234:235], v1 offset:0x3800
	v_bitop3_b32 v87, v72, s74, v84 bitop3:0xe4
	v_bfe_i32 v84, v160, 11, 1
	v_bitop3_b32 v72, v88, s74, v85 bitop3:0xe4
	v_bfe_i32 v85, v161, 11, 1
	v_bitop3_b32 v88, v73, s74, v84 bitop3:0xe4
	v_bfe_i32 v73, v160, 16, 1
	v_bitop3_b32 v84, v89, s74, v85 bitop3:0xe4
	s_waitcnt lgkmcnt(12)
	v_mfma_f32_32x32x16_bf16 v[34:49], v[152:155], v[236:239], v[34:49]
	ds_read_b64_tr_b16 v[236:237], v1 offset:0x3200
	ds_read_b64_tr_b16 v[238:239], v1 offset:0x3a00
	v_bfe_i32 v85, v161, 16, 1
	v_bitop3_b32 v89, v74, s74, v73 bitop3:0xe4
	v_bfe_i32 v73, v160, 17, 1
	v_bfe_i32 v74, v161, 17, 1
	v_bitop3_b32 v85, v90, s74, v85 bitop3:0xe4
	v_bitop3_b32 v90, v75, s74, v73 bitop3:0xe4
	s_waitcnt lgkmcnt(12)
	v_mfma_f32_32x32x16_bf16 v[18:33], v[152:155], v[240:243], v[18:33]
	ds_read_b64_tr_b16 v[240:241], v1 offset:0x3400
	ds_read_b64_tr_b16 v[242:243], v1 offset:0x3c00
	v_bitop3_b32 v86, v91, s74, v74 bitop3:0xe4
	v_bfe_i32 v73, v160, 18, 1
	v_bfe_i32 v74, v161, 18, 1
	v_bitop3_b32 v91, v76, s74, v73 bitop3:0xe4
	v_bitop3_b32 v76, v92, s74, v74 bitop3:0xe4
	v_bfe_i32 v73, v160, 19, 1
	v_bfe_i32 v74, v161, 19, 1
	s_waitcnt lgkmcnt(12)
	v_mfma_f32_32x32x16_bf16 v[2:17], v[156:159], v[244:247], v[2:17]
	ds_read_b64_tr_b16 v[244:245], v1 offset:0x3600
	ds_read_b64_tr_b16 v[246:247], v1 offset:0x3e00
	v_bitop3_b32 v92, v77, s74, v73 bitop3:0xe4
	v_bitop3_b32 v77, v93, s74, v74 bitop3:0xe4
	v_bfe_i32 v73, v160, 24, 1
	v_bfe_i32 v74, v161, 24, 1
	v_bitop3_b32 v93, v78, s74, v73 bitop3:0xe4
	v_bitop3_b32 v78, v94, s74, v74 bitop3:0xe4
	s_waitcnt lgkmcnt(12)
	v_mfma_f32_32x32x16_bf16 v[50:65], v[156:159], v[248:251], v[50:65]
	v_bfe_i32 v73, v160, 25, 1
	v_bfe_i32 v74, v161, 25, 1
	v_bitop3_b32 v79, v79, s74, v73 bitop3:0xe4
	v_bitop3_b32 v73, v95, s74, v74 bitop3:0xe4
	v_bfe_i32 v74, v160, 26, 1
	v_bfe_i32 v75, v161, 26, 1
	v_bitop3_b32 v80, v80, s74, v74 bitop3:0xe4
	s_waitcnt lgkmcnt(10)
	v_mfma_f32_32x32x16_bf16 v[34:49], v[156:159], v[220:223], v[34:49]
	v_bitop3_b32 v74, v96, s74, v75 bitop3:0xe4
	v_bfe_i32 v75, v160, 27, 1
	v_bfe_i32 v94, v161, 27, 1
	v_bitop3_b32 v81, v81, s74, v75 bitop3:0xe4
	v_bitop3_b32 v75, v97, s74, v94 bitop3:0xe4
	v_max_f32_e32 v94, v82, v82
	s_waitcnt lgkmcnt(8)
	v_mfma_f32_32x32x16_bf16 v[18:33], v[156:159], v[224:227], v[18:33]
	v_max_f32_e32 v95, v146, v146
	v_max_f32_e32 v94, v95, v94
	v_max3_f32 v94, v94, v83, v147
	v_max3_f32 v94, v94, v148, v149
	v_max3_f32 v94, v94, v87, v88
	v_max3_f32 v94, v94, v89, v90
	v_max3_f32 v94, v94, v91, v92
	s_waitcnt lgkmcnt(6)
	v_mfma_f32_32x32x16_bf16 v[2:17], v[208:211], v[232:235], v[2:17]
	v_max3_f32 v94, v94, v93, v79
	v_max3_f32 v94, v94, v80, v81
	v_max3_f32 v94, v94, v66, v67
	v_max3_f32 v94, v94, v68, v69
	v_max3_f32 v94, v94, v70, v71
	v_max3_f32 v94, v94, v72, v84
	s_waitcnt lgkmcnt(4)
	v_mfma_f32_32x32x16_bf16 v[50:65], v[208:211], v[236:239], v[50:65]
	v_max3_f32 v94, v94, v85, v86
	v_max3_f32 v94, v94, v76, v77
	v_max3_f32 v94, v94, v78, v73
	v_max3_f32 v94, v94, v74, v75
	v_mov_b32_e32 v95, v94
	s_nop 1
	v_permlane32_swap_b32_e32 v94, v95
	s_waitcnt lgkmcnt(2)
	v_mfma_f32_32x32x16_bf16 v[34:49], v[208:211], v[240:243], v[34:49]
	v_max_f32_e32 v95, v95, v95
	v_max_f32_e32 v94, v94, v94
	v_max_f32_e32 v94, v94, v95
	v_max_f32_e32 v96, v206, v206
	v_sub_f32_e32 v95, v94, v206
	v_max_f32_e32 v94, v96, v94
	v_sub_f32_e32 v96, v206, v94
	s_waitcnt lgkmcnt(0)
	v_mfma_f32_32x32x16_bf16 v[18:33], v[208:211], v[244:247], v[18:33]
	v_mul_f32_e32 v96, 0x3e0293ee, v96
	v_mul_f32_e32 v95, 0x3db504f3, v95
	v_exp_f32_e32 v96, v96
	v_cmp_ge_f32_e32 vcc, s75, v95
	s_cmp_eq_u64 vcc, exec
	s_cselect_b64 s[6:7], -1, 0
	s_barrier
	s_waitcnt vmcnt(0)
	v_cndmask_b32_e64 v208, v96, 1.0, s[6:7]
	v_cmp_gt_f32_e32 vcc, 1.0, v208
	ds_write_b128 v197, v[130:133]
	ds_write_b128 v198, v[134:137]
	ds_write_b128 v204, v[138:141] offset:32768
	ds_write_b128 v204, v[142:145] offset:40960
	s_cbranch_vccz .LBB0_1303
	s_and_saveexec_b64 s[36:37], s[0:1]
	ds_write_b32 v185, v208 offset:128
	s_or_b64 exec, exec, s[36:37]
	s_waitcnt lgkmcnt(0)
	ds_read_b128 v[150:153], v183 offset:224
	ds_read_b128 v[154:157], v183 offset:192
	ds_read_b128 v[158:161], v183 offset:160
	ds_read_b128 v[172:175], v183 offset:128
	s_waitcnt lgkmcnt(3)
	v_pk_mul_f32 v[16:17], v[16:17], v[152:153]
	s_waitcnt lgkmcnt(2)
	v_pk_mul_f32 v[12:13], v[12:13], v[156:157]
	s_waitcnt lgkmcnt(1)
	v_pk_mul_f32 v[8:9], v[8:9], v[160:161]
	s_waitcnt lgkmcnt(0)
	v_pk_mul_f32 v[4:5], v[4:5], v[174:175]
	v_pk_mul_f32 v[14:15], v[14:15], v[150:151]
	v_pk_mul_f32 v[10:11], v[10:11], v[154:155]
	v_pk_mul_f32 v[6:7], v[6:7], v[158:159]
	v_pk_mul_f32 v[2:3], v[2:3], v[172:173]
	v_pk_mul_f32 v[64:65], v[64:65], v[152:153]
	v_pk_mul_f32 v[60:61], v[60:61], v[156:157]
	v_pk_mul_f32 v[56:57], v[56:57], v[160:161]
	v_pk_mul_f32 v[52:53], v[52:53], v[174:175]
	v_pk_mul_f32 v[62:63], v[62:63], v[150:151]
	v_pk_mul_f32 v[58:59], v[58:59], v[154:155]
	v_pk_mul_f32 v[54:55], v[54:55], v[158:159]
	v_pk_mul_f32 v[50:51], v[50:51], v[172:173]
	v_pk_mul_f32 v[48:49], v[48:49], v[152:153]
	v_pk_mul_f32 v[44:45], v[44:45], v[156:157]
	v_pk_mul_f32 v[40:41], v[40:41], v[160:161]
	v_pk_mul_f32 v[36:37], v[36:37], v[174:175]
	v_pk_mul_f32 v[46:47], v[46:47], v[150:151]
	v_pk_mul_f32 v[42:43], v[42:43], v[154:155]
	v_pk_mul_f32 v[38:39], v[38:39], v[158:159]
	v_pk_mul_f32 v[34:35], v[34:35], v[172:173]
	v_pk_mul_f32 v[32:33], v[32:33], v[152:153]
	v_pk_mul_f32 v[28:29], v[28:29], v[156:157]
	v_pk_mul_f32 v[24:25], v[24:25], v[160:161]
	v_pk_mul_f32 v[20:21], v[20:21], v[174:175]
	v_pk_mul_f32 v[30:31], v[30:31], v[150:151]
	v_pk_mul_f32 v[26:27], v[26:27], v[154:155]
	v_pk_mul_f32 v[22:23], v[22:23], v[158:159]
	v_pk_mul_f32 v[18:19], v[18:19], v[172:173]

; __device__ __forceinline__ void sel_mask_tile(f32x16& p0, f32x16& p1, unsigned wlo, unsigned whi, int hi) {
;     const unsigned NEGB = 0xff800000u;
;     const unsigned lo = wlo >> (4 * hi), h2 = whi >> (4 * hi);
; #pragma unroll
;     for (int r = 0; r < 16; ++r) {
;         const int c = (r & 3) + 8 * (r >> 2);
;         const unsigned m0 = (unsigned)__builtin_amdgcn_sbfe((int)lo, c, 1), m1 = (unsigned)__builtin_amdgcn_sbfe((int)h2, c, 1);
;         p0[r] = __uint_as_float((__float_as_uint(p0[r]) & m0) | (NEGB & ~m0));
;         p1[r] = __uint_as_float((__float_as_uint(p1[r]) & m1) | (NEGB & ~m1));
;     }
; }
; __device__ __forceinline__ void partialSM(f32x16& p0, f32x16& p1, float& m_reg, float& mn, float& alpha) {
;     float pmax = p0[0];
; #pragma unroll
;     for (int r = 1; r < 16; ++r) pmax = fmaxf(pmax, p0[r]);
; #pragma unroll
;     for (int r = 0; r < 16; ++r) pmax = fmaxf(pmax, p1[r]);
;     { auto rr = __builtin_amdgcn_permlane32_swap(__float_as_uint(pmax), __float_as_uint(pmax), false, false);
;       pmax = fmaxf(__uint_as_float(rr[0]), __uint_as_float(rr[1])); }
;     constexpr float C2 = 1.4426950408889634f * SCALE;
;     if (__builtin_expect(__all((pmax - m_reg) * SCALE <= THR), 1)) { mn = m_reg; alpha = 1.f; }
;     else { mn = fmaxf(m_reg, pmax); alpha = __builtin_amdgcn_exp2f((m_reg - mn) * C2); m_reg = mn; }
; template <int VB>
; __device__ __forceinline__ void pv_tile(f32x16* o, int vb0, bf16x8 pa0, bf16x8 pa1, bf16x8 pa2, bf16x8 pa3) {
;     ...
;     PV_D0(0); PV_D0(1); PV_D0(2); PV_D0(3);
;     ...
; }
.LBB0_1305:
	ds_read_b64_tr_b16 v[212:213], v1 offset:0x4000
	ds_read_b64_tr_b16 v[214:215], v1 offset:0x4800
	ds_read_b64_tr_b16 v[216:217], v1 offset:0x4200
	ds_read_b64_tr_b16 v[218:219], v1 offset:0x4a00
	ds_read_b64_tr_b16 v[220:221], v1 offset:0x4400
	ds_read_b64_tr_b16 v[222:223], v1 offset:0x4c00
	ds_read_b64_tr_b16 v[224:225], v1 offset:0x4600
	ds_read_b64_tr_b16 v[226:227], v1 offset:0x4e00
	ds_read_b64_tr_b16 v[232:233], v1 offset:0x5000
	ds_read_b64_tr_b16 v[234:235], v1 offset:0x5800
	ds_read_b64_tr_b16 v[236:237], v1 offset:0x5200
	ds_read_b64_tr_b16 v[238:239], v1 offset:0x5a00
	ds_read_b64_tr_b16 v[240:241], v1 offset:0x5400
	ds_read_b64_tr_b16 v[242:243], v1 offset:0x5c00
	s_nop 0
	s_waitcnt lgkmcnt(12)
	v_mfma_f32_32x32x16_bf16 v[2:17], v[146:149], v[212:215], v[2:17]
	ds_read_b64_tr_b16 v[244:245], v1 offset:0x5600
	ds_read_b64_tr_b16 v[246:247], v1 offset:0x5e00
	s_waitcnt vmcnt(4)
	v_lshrrev_b32_e32 v193, v163, v228
	v_bfe_i32 v192, v193, 0, 1
	v_bitop3_b32 v192, v82, s74, v192 bitop3:0xe4
	v_bfe_i32 v82, v193, 1, 1
	s_waitcnt lgkmcnt(12)
	v_mfma_f32_32x32x16_bf16 v[50:65], v[146:149], v[216:219], v[50:65]
	ds_read_b64_tr_b16 v[248:249], v1 offset:0x6000
	ds_read_b64_tr_b16 v[250:251], v1 offset:0x6800
	s_waitcnt lgkmcnt(12)
	v_mfma_f32_32x32x16_bf16 v[34:49], v[146:149], v[220:223], v[34:49]
	ds_read_b64_tr_b16 v[220:221], v1 offset:0x6200
	ds_read_b64_tr_b16 v[222:223], v1 offset:0x6a00
	s_waitcnt lgkmcnt(12)
	v_mfma_f32_32x32x16_bf16 v[18:33], v[146:149], v[224:227], v[18:33]
	ds_read_b64_tr_b16 v[224:225], v1 offset:0x6400
	ds_read_b64_tr_b16 v[226:227], v1 offset:0x6c00
	v_bitop3_b32 v146, v83, s74, v82 bitop3:0xe4
	v_bfe_i32 v82, v193, 2, 1
	v_bitop3_b32 v147, v84, s74, v82 bitop3:0xe4
	v_bfe_i32 v82, v193, 3, 1
	v_bitop3_b32 v148, v85, s74, v82 bitop3:0xe4
	v_bfe_i32 v82, v193, 8, 1
	v_bitop3_b32 v149, v86, s74, v82 bitop3:0xe4
	s_waitcnt lgkmcnt(12)
	v_mfma_f32_32x32x16_bf16 v[2:17], v[150:153], v[232:235], v[2:17]
	ds_read_b64_tr_b16 v[232:233], v1 offset:0x6600
	ds_read_b64_tr_b16 v[234:235], v1 offset:0x6e00
	v_bfe_i32 v82, v193, 9, 1
	s_waitcnt lgkmcnt(12)
	v_mfma_f32_32x32x16_bf16 v[50:65], v[150:153], v[236:239], v[50:65]
	ds_read_b64_tr_b16 v[236:237], v1 offset:0x7000
	ds_read_b64_tr_b16 v[238:239], v1 offset:0x7800
	s_waitcnt lgkmcnt(12)
	v_mfma_f32_32x32x16_bf16 v[34:49], v[150:153], v[240:243], v[34:49]
	ds_read_b64_tr_b16 v[240:241], v1 offset:0x7200
	ds_read_b64_tr_b16 v[242:243], v1 offset:0x7a00
	s_waitcnt lgkmcnt(12)
	v_mfma_f32_32x32x16_bf16 v[18:33], v[150:153], v[244:247], v[18:33]
	ds_read_b64_tr_b16 v[244:245], v1 offset:0x7400
	ds_read_b64_tr_b16 v[246:247], v1 offset:0x7c00
	v_bitop3_b32 v150, v87, s74, v82 bitop3:0xe4
	v_bfe_i32 v82, v193, 10, 1
	v_bitop3_b32 v88, v88, s74, v82 bitop3:0xe4
	v_bfe_i32 v82, v193, 11, 1
	v_bitop3_b32 v89, v89, s74, v82 bitop3:0xe4
	v_bfe_i32 v82, v193, 16, 1
	v_bitop3_b32 v90, v90, s74, v82 bitop3:0xe4
	v_bfe_i32 v82, v193, 17, 1
	v_bitop3_b32 v91, v91, s74, v82 bitop3:0xe4
	s_waitcnt lgkmcnt(12)
	v_mfma_f32_32x32x16_bf16 v[2:17], v[154:157], v[248:251], v[2:17]
	ds_read_b64_tr_b16 v[248:249], v1 offset:0x7600
	ds_read_b64_tr_b16 v[250:251], v1 offset:0x7e00
	v_bfe_i32 v82, v193, 18, 1
	v_bitop3_b32 v92, v92, s74, v82 bitop3:0xe4
	v_bfe_i32 v82, v193, 19, 1
	v_bitop3_b32 v93, v93, s74, v82 bitop3:0xe4
	v_bfe_i32 v82, v193, 24, 1
	v_bitop3_b32 v94, v94, s74, v82 bitop3:0xe4
	v_bfe_i32 v82, v193, 25, 1
	v_bitop3_b32 v95, v95, s74, v82 bitop3:0xe4
	v_bfe_i32 v82, v193, 26, 1
	s_waitcnt lgkmcnt(12)
	v_mfma_f32_32x32x16_bf16 v[50:65], v[154:157], v[220:223], v[50:65]
	v_bitop3_b32 v96, v96, s74, v82 bitop3:0xe4
	v_bfe_i32 v82, v193, 27, 1
	v_bitop3_b32 v97, v97, s74, v82 bitop3:0xe4
	v_max_f32_e32 v82, v146, v146
	v_max_f32_e32 v230, v192, v192
	v_max_f32_e32 v82, v230, v82
	v_max3_f32 v82, v82, v147, v148
	v_max3_f32 v82, v82, v149, v150
	v_max3_f32 v82, v82, v88, v89
	s_waitcnt lgkmcnt(10)
	v_mfma_f32_32x32x16_bf16 v[34:49], v[154:157], v[224:227], v[34:49]
	v_max3_f32 v82, v82, v90, v91
	v_lshrrev_b32_e32 v194, v163, v229
	v_max3_f32 v82, v82, v92, v93
	v_bfe_i32 v195, v194, 0, 1
	v_bfe_i32 v172, v194, 1, 1
	v_max3_f32 v82, v82, v94, v95
	v_bitop3_b32 v66, v66, s74, v195 bitop3:0xe4
	v_bfe_i32 v83, v194, 2, 1
	v_bfe_i32 v84, v194, 3, 1
	s_waitcnt lgkmcnt(8)
	v_mfma_f32_32x32x16_bf16 v[18:33], v[154:157], v[232:235], v[18:33]
	v_max3_f32 v230, v82, v96, v97
	v_bitop3_b32 v67, v67, s74, v172 bitop3:0xe4
	v_bfe_i32 v85, v194, 8, 1
	v_bfe_i32 v86, v194, 9, 1
	v_bitop3_b32 v82, v68, s74, v83 bitop3:0xe4
	v_max3_f32 v68, v230, v66, v67
	v_bitop3_b32 v83, v69, s74, v84 bitop3:0xe4
	v_bfe_i32 v87, v194, 10, 1
	v_bfe_i32 v151, v194, 11, 1
	s_waitcnt lgkmcnt(6)
	v_mfma_f32_32x32x16_bf16 v[2:17], v[158:161], v[236:239], v[2:17]
	v_bitop3_b32 v84, v70, s74, v85 bitop3:0xe4
	v_max3_f32 v68, v68, v82, v83
	v_bitop3_b32 v85, v71, s74, v86 bitop3:0xe4
	v_bfe_i32 v152, v194, 16, 1
	v_bfe_i32 v153, v194, 17, 1
	v_bitop3_b32 v86, v72, s74, v87 bitop3:0xe4
	v_max3_f32 v68, v68, v84, v85
	v_bitop3_b32 v87, v73, s74, v151 bitop3:0xe4
	v_bfe_i32 v154, v194, 18, 1
	s_waitcnt lgkmcnt(4)
	v_mfma_f32_32x32x16_bf16 v[50:65], v[158:161], v[240:243], v[50:65]
	v_bfe_i32 v155, v194, 19, 1
	v_bitop3_b32 v74, v74, s74, v152 bitop3:0xe4
	v_max3_f32 v69, v68, v86, v87
	v_bitop3_b32 v75, v75, s74, v153 bitop3:0xe4
	v_bfe_i32 v156, v194, 24, 1
	v_bfe_i32 v157, v194, 25, 1
	v_bitop3_b32 v68, v76, s74, v154 bitop3:0xe4
	v_max3_f32 v71, v69, v74, v75
	v_bitop3_b32 v69, v77, s74, v155 bitop3:0xe4
	s_waitcnt lgkmcnt(2)
	v_mfma_f32_32x32x16_bf16 v[34:49], v[158:161], v[244:247], v[34:49]
	v_bfe_i32 v230, v194, 26, 1
	v_bfe_i32 v231, v194, 27, 1
	v_bitop3_b32 v70, v78, s74, v156 bitop3:0xe4
	v_max3_f32 v73, v71, v68, v69
	v_bitop3_b32 v71, v79, s74, v157 bitop3:0xe4
	v_bitop3_b32 v72, v80, s74, v230 bitop3:0xe4
	v_max3_f32 v76, v73, v70, v71
	v_bitop3_b32 v73, v81, s74, v231 bitop3:0xe4
	v_max3_f32 v76, v76, v72, v73
	v_mov_b32_e32 v77, v76
	s_waitcnt lgkmcnt(0)
	v_mfma_f32_32x32x16_bf16 v[18:33], v[158:161], v[248:251], v[18:33]
	s_nop 1
	v_permlane32_swap_b32_e32 v76, v77
	v_max_f32_e32 v77, v77, v77
	v_max_f32_e32 v76, v76, v76
	v_max_f32_e32 v76, v76, v77
	v_sub_f32_e32 v77, v76, v206
	v_mul_f32_e32 v77, 0x3db504f3, v77
	v_cmp_ge_f32_e32 vcc, s75, v77
	s_cmp_eq_u64 vcc, exec
	s_cselect_b64 s[6:7], -1, 0
	s_andn2_b64 vcc, exec, s[36:37]
	s_barrier
	s_cbranch_vccnz .LBB0_1307
	s_waitcnt vmcnt(0)
	ds_write_b128 v197, v[130:133] offset:16384
	ds_write_b128 v198, v[134:137] offset:16384
	ds_write_b128 v204, v[138:141] offset:49152
	ds_write_b128 v204, v[142:145] offset:57344
